# P6 K-loop: LDS-DMA loads use saddr form, no VALU in load segments, A0 staging moved to SP1 (4+4 balance), vmcnt 8/6
# speedup vs baseline: 1.0048x; 1.0048x over previous
; #define PG8_STAGE(bufoff, gbase, voff) do { _Pragma("unroll") for (int _i = 0; _i < 2; ++_i) \
;         __builtin_amdgcn_global_load_lds((const unsigned*)((const char*)(gbase) + (voff)[_i]), (PG8_LAS unsigned*)(lds + (bufoff) + ldsw + _i * 8192), 16, 0, 0); } while (0)
; #define PG8_WAIT_V(n) asm volatile("s_waitcnt vmcnt(" #n ")" ::: "memory")
; #define PG8_BAR __builtin_amdgcn_s_barrier()
; template <class Epi, class Sched, bool ALIGN_EPI = false, bool SP2 = false>
; __device__ __forceinline__ void gemm_phase(PG8_LAS unsigned char* lds, const Gemm g, const Sched& S, const Epi& E) {
;     const int tid = threadIdx.x, wid = __builtin_amdgcn_readfirstlane(tid >> 6), lane = tid & 63, wr = wid >> 2, wc = wid & 3, fr = lane & 15, fq = lane >> 4;
;     const int K = g.K, nt = K / BK;
;     unsigned voffA[2], voffB[2];
; #pragma unroll
;     for (int i = 0; i < 2; ++i) { int R, C; stage_rc(tid * 16 + i * 8192, R, C); const int Rb = Epi::PERM ? ((R & ~31) + perm32(R & 31)) : R;
;         voffA[i] = (unsigned)(R * K + C) * 2u; voffB[i] = (unsigned)(Rb * K + C) * 2u; }
;     const size_t kstep = (size_t)(BK * 2);
;     const size_t hstep = (size_t)HALF * K * 2;
;     const size_t tstep = 2 * hstep;
;     const unsigned ldsw = (unsigned)wid * 1024u;
;     const int aoff = lds_byte(wr * 64 + fr, fq * 8), boff = lds_byte(wc * 32 + fr, fq * 8);
;     ...
;     Unit cur, nxt; int ui = 0;
;     if (!S.next(0, cur)) return;
;     f32x4 acc[2][2][4][2];
; #pragma unroll
;     for (int a = 0; a < 2; ++a)
; #pragma unroll
;         for (int b = 0; b < 2; ++b)
; #pragma unroll
;             for (int m = 0; m < 4; ++m)
; #pragma unroll
;                 for (int n = 0; n < 2; ++n) acc[a][b][m][n] = (f32x4){0.f, 0.f, 0.f, 0.f};
;     bf16x8 At[4][2], B0[2][2], B1[2][2];
;     const char* cA = (const char*)g.A + (size_t)cur.pm * tstep; const char* cB = (const char*)g.Bt + (size_t)cur.pn * tstep;
;     S.a_ready(cur);
;     if constexpr (SP2) {
;         PG8_STAGE(PG8_SB(0, 0), cB, voffB); PG8_STAGE(PG8_SB(0, 1), cB + hstep, voffB); PG8_STAGE(PG8_SA(0, 0), cA, voffA); PG8_STAGE(PG8_SA(0, 1), cA + hstep, voffA);
;         if (wr == 1) PG8_BAR;
;         PG8_WAIT_V(2); PG8_BAR;
;         PG8_STAGE(PG8_SB(1, 0), cB + kstep, voffB); PG8_STAGE(PG8_SA(1, 0), cA + kstep, voffA); PG8_STAGE(PG8_SB(1, 1), cB + hstep + kstep, voffB);
;         PG8_WAIT_V(6); PG8_BAR;
.LBB0_686:
	s_lshl_b32 s6, s6, 5
	s_and_b32 s21, s6, 0x60
	s_mov_b64 s[6:7], 0x80
	s_add_i32 m0, s23, 0x18000
	v_lshl_add_u64 v[8:9], v[8:9], 0, s[6:7]
	s_lshl_b32 s20, s16, 13
	s_lshl_b32 s36, s21, 7
	s_waitcnt vmcnt(2)
	s_barrier
	global_load_lds_dwordx4 v[8:9], off
	v_lshl_add_u64 v[6:7], v[6:7], 0, s[6:7]
	s_add_i32 m0, s23, 0x1a000
	s_add_i32 s49, s23, 0x8000
	s_add_i32 s50, s23, 0xa000
	global_load_lds_dwordx4 v[6:7], off
	v_lshl_add_u64 v[2:3], v[2:3], 0, s[6:7]
	s_mov_b32 m0, s49
	s_add_u32 s18, s24, 0x80080
	global_load_lds_dwordx4 v[2:3], off
	v_lshl_add_u64 v[2:3], v[4:5], 0, s[6:7]
	s_mov_b32 m0, s50
	s_addc_u32 s19, s25, 0
	global_load_lds_dwordx4 v[2:3], off
	s_add_i32 m0, s23, 0x1c000
	v_lshl_add_u64 v[2:3], s[18:19], 0, v[134:135]
	global_load_lds_dwordx4 v[2:3], off
	v_lshl_add_u64 v[2:3], s[18:19], 0, v[130:131]
	s_add_i32 m0, s23, 0x1e000
	s_sext_i32_i16 s57, s12
	global_load_lds_dwordx4 v[2:3], off
	v_and_b32_e32 v3, 15, v200
	v_and_b32_e32 v2, 48, v200
	v_lshlrev_b32_e32 v154, 2, v3
	v_lshl_or_b32 v153, s16, 6, v3
	v_lshl_or_b32 v4, v3, 6, v2
	v_and_b32_e32 v3, 32, v154
	v_bitop3_b32 v4, v4, s20, v3 bitop3:0xde
	v_lshlrev_b32_e32 v3, 6, v200
	s_movk_i32 s12, 0x3c0
	s_cmpk_lt_u32 s13, 0x100
	v_and_or_b32 v3, v3, s12, v2
	s_cselect_b64 s[12:13], -1, 0
	s_ashr_i32 s51, s11, 31
	s_add_u32 s14, s14, s17
	s_addc_u32 s15, s15, 0
	v_lshlrev_b32_e32 v5, 2, v200
	v_lshl_add_u64 v[140:141], s[14:15], 0, v[138:139]
	s_lshl_b32 s14, s21, 1
	v_and_b32_e32 v5, 32, v5
	s_add_u32 s2, s2, s14
	v_bitop3_b32 v155, s36, v3, v5 bitop3:0xf6
	v_add_u32_e32 v238, 0x10000, v155
	s_addc_u32 s3, s3, 0
	v_mov_b32_e32 v3, v139
	v_lshl_add_u64 v[2:3], s[2:3], 0, v[2:3]
	s_mov_b64 s[2:3], 0xe800000
	v_lshl_add_u64 v[142:143], v[2:3], 0, s[2:3]
	v_lshlrev_b32_e32 v2, 5, v12
	v_and_b32_e32 v2, 0xf0000, v2
	v_lshlrev_b32_e32 v3, 12, v13
	v_or3_b32 v2, v10, v2, v3
	v_add_u32_e32 v138, v2, v11
	v_lshlrev_b32_e32 v2, 9, v200
	s_waitcnt vmcnt(6)
	v_and_b32_e32 v2, 0x70000, v2
	v_or3_b32 v2, v10, v2, v3
	v_or_b32_e32 v156, 64, v154
	v_or_b32_e32 v157, 0x80, v154
	v_or_b32_e32 v158, 0xc0, v154
	v_add_u32_e32 v144, v2, v11
	v_mov_b32_e32 v145, v139
	v_mov_b64_e32 v[146:147], 0x1600
	v_mov_b64_e32 v[148:149], 0x15ff
	s_add_i32 s52, 0, 0x10000
	s_add_i32 s53, 0, 0x14000
	v_add_u32_e32 v159, 0, v4
	s_movk_i32 s54, 0x2c00
	v_mov_b32_e32 v160, v139
	v_mov_b32_e32 v161, v139
	s_barrier
	s_branch .LBB0_689

; #define PG8_STAGE(bufoff, gbase, voff) do { _Pragma("unroll") for (int _i = 0; _i < 2; ++_i) \
;         __builtin_amdgcn_global_load_lds((const unsigned*)((const char*)(gbase) + (voff)[_i]), (PG8_LAS unsigned*)(lds + (bufoff) + ldsw + _i * 8192), 16, 0, 0); } while (0)
; #define PG8_LDA(dst, b, h) do { _Pragma("unroll") for (int m = 0; m < 4; ++m) _Pragma("unroll") for (int k = 0; k < 2; ++k) dst[m][k] = *(const PG8_LAS bf16x8*)(lds + PG8_SA(b, h) + aoff + m * 2048 + k * 1024); } while (0)
; #define PG8_LDB(dst, b, h) do { _Pragma("unroll") for (int n = 0; n < 2; ++n) _Pragma("unroll") for (int k = 0; k < 2; ++k) dst[n][k] = *(const PG8_LAS bf16x8*)(lds + PG8_SB(b, h) + boff + n * 2048 + k * 1024); } while (0)
; #define PG8_MMA(ai, bj, At, Bt) do { __builtin_amdgcn_s_setprio(1); _Pragma("unroll") for (int m = 0; m < 4; ++m) _Pragma("unroll") for (int n = 0; n < 2; ++n) _Pragma("unroll") for (int k = 0; k < 2; ++k) \
;         acc[ai][bj][m][n] = __builtin_amdgcn_mfma_f32_16x16x32_bf16(Bt[n][k], At[m][k], acc[ai][bj][m][n], 0, 0, 0); __builtin_amdgcn_s_setprio(0); } while (0)
; #define PG8_WAIT_V(n) asm volatile("s_waitcnt vmcnt(" #n ")" ::: "memory")
; #define PG8_BAR __builtin_amdgcn_s_barrier()
; template <class Epi, class Sched, bool ALIGN_EPI = false, bool SP2 = false>
; __device__ __forceinline__ void gemm_phase(PG8_LAS unsigned char* lds, const Gemm g, const Sched& S, const Epi& E) {
;     ...
;         for (int t = 0; t < nt; t += 2) {
;             const bool last = (t == nt - 2);
;             const char* a1 = cA + (size_t)(t + 1) * kstep;
;             const char* a2 = last ? nA : cA + (size_t)(t + 2) * kstep; const char* b2 = last ? nB : cB + (size_t)(t + 2) * kstep;
;             const char* a3 = a2 + kstep; const char* b3 = b2 + kstep;
;             if (last && has_next) S.a_ready(nxt);
;             if constexpr (SP2) {
;             PG8_LDB(B0, 0, 0); PG8_LDB(B1, 0, 1); PG8_SCHED; PG8_LDA(At, 0, 0); PG8_STAGE(PG8_SA(1, 1), a1 + hstep, voffA);
;             PG8_WAIT_V(8); PG8_WAIT_L(0); PG8_BAR; PG8_MMA(0, 0, At, B0); PG8_MMA(0, 1, At, B1); PG8_BAR; PG8_SCHED;
;             PG8_LDA(At, 0, 1); PG8_STAGE(PG8_SB(0, 0), b2, voffB); PG8_STAGE(PG8_SB(0, 1), b2 + hstep, voffB); PG8_STAGE(PG8_SA(0, 0), a2, voffA);
;             PG8_WAIT_V(8); PG8_WAIT_L(0); PG8_BAR; PG8_MMA(1, 0, At, B0); PG8_MMA(1, 1, At, B1); PG8_BAR; PG8_SCHED;
.LBB0_692:
	ds_read_b128 v[162:165], v238
	ds_read_b128 v[166:169], v238 offset:1024
	ds_read_b128 v[170:173], v238 offset:2048
	ds_read_b128 v[174:177], v238 offset:3072
	ds_read_b128 v[178:181], v238 offset:16384
	ds_read_b128 v[182:185], v238 offset:17408
	ds_read_b128 v[186:189], v238 offset:18432
	ds_read_b128 v[190:193], v238 offset:19456
	s_add_u32 s36, s24, 0xfff80080
	s_addc_u32 s37, s25, -1
	s_and_b64 s[26:27], s[26:27], exec
	s_cselect_b32 s37, s17, s37
	s_cselect_b32 s36, s60, s36
	s_cselect_b32 s27, s15, s63
	s_cselect_b32 s26, s61, s62
	s_add_u32 s68, s24, 0xfff80000
	s_addc_u32 s69, s25, -1
	s_mov_b32 m0, s49
	s_nop 0
	global_load_lds_dwordx4 v136, s[68:69]
	s_mov_b32 m0, s50
	s_nop 0
	global_load_lds_dwordx4 v132, s[68:69]
	s_add_i32 m0, s23, 0xc000
	ds_read_b128 v[194:197], v159
	ds_read_b128 v[202:205], v159 offset:1024
	ds_read_b128 v[206:209], v159 offset:2048
	ds_read_b128 v[210:213], v159 offset:3072
	ds_read_b128 v[214:217], v159 offset:4096
	ds_read_b128 v[218:221], v159 offset:5120
	ds_read_b128 v[222:225], v159 offset:6144
	ds_read_b128 v[226:229], v159 offset:7168
	global_load_lds_dwordx4 v144, s[24:25]
	s_add_i32 m0, s23, 0xe000
	s_nop 0
	global_load_lds_dwordx4 v138, s[24:25]
	s_waitcnt vmcnt(8)
	s_waitcnt lgkmcnt(0)
	s_barrier
	s_setprio 1
	s_waitcnt lgkmcnt(0)
	v_mfma_f32_16x16x32_bf16 v[126:129], v[162:165], v[194:197], v[126:129]
	v_mfma_f32_16x16x32_bf16 v[118:121], v[170:173], v[194:197], v[118:121]
	v_mfma_f32_16x16x32_bf16 v[110:113], v[162:165], v[206:209], v[110:113]
	v_mfma_f32_16x16x32_bf16 v[102:105], v[170:173], v[206:209], v[102:105]
	v_mfma_f32_16x16x32_bf16 v[94:97], v[162:165], v[214:217], v[94:97]
	v_mfma_f32_16x16x32_bf16 v[86:89], v[170:173], v[214:217], v[86:89]
	v_mfma_f32_16x16x32_bf16 v[78:81], v[162:165], v[222:225], v[78:81]
	v_mfma_f32_16x16x32_bf16 v[70:73], v[170:173], v[222:225], v[70:73]
	v_mfma_f32_16x16x32_bf16 v[126:129], v[166:169], v[202:205], v[126:129]
	v_mfma_f32_16x16x32_bf16 v[118:121], v[174:177], v[202:205], v[118:121]
	v_mfma_f32_16x16x32_bf16 v[110:113], v[166:169], v[210:213], v[110:113]
	v_mfma_f32_16x16x32_bf16 v[102:105], v[174:177], v[210:213], v[102:105]
	v_mfma_f32_16x16x32_bf16 v[94:97], v[166:169], v[218:221], v[94:97]
	v_mfma_f32_16x16x32_bf16 v[86:89], v[174:177], v[218:221], v[86:89]
	v_mfma_f32_16x16x32_bf16 v[78:81], v[166:169], v[226:229], v[78:81]
	v_mfma_f32_16x16x32_bf16 v[70:73], v[174:177], v[226:229], v[70:73]
	s_setprio 0
	s_setprio 1
	v_mfma_f32_16x16x32_bf16 v[122:125], v[178:181], v[194:197], v[122:125]
	v_mfma_f32_16x16x32_bf16 v[114:117], v[186:189], v[194:197], v[114:117]
	v_mfma_f32_16x16x32_bf16 v[106:109], v[178:181], v[206:209], v[106:109]
	v_mfma_f32_16x16x32_bf16 v[98:101], v[186:189], v[206:209], v[98:101]
	v_mfma_f32_16x16x32_bf16 v[90:93], v[178:181], v[214:217], v[90:93]
	v_mfma_f32_16x16x32_bf16 v[82:85], v[186:189], v[214:217], v[82:85]
	v_mfma_f32_16x16x32_bf16 v[74:77], v[178:181], v[222:225], v[74:77]
	v_mfma_f32_16x16x32_bf16 v[66:69], v[186:189], v[222:225], v[66:69]
	v_mfma_f32_16x16x32_bf16 v[122:125], v[182:185], v[202:205], v[122:125]
	v_mfma_f32_16x16x32_bf16 v[114:117], v[190:193], v[202:205], v[114:117]
	v_mfma_f32_16x16x32_bf16 v[106:109], v[182:185], v[210:213], v[106:109]
	v_mfma_f32_16x16x32_bf16 v[98:101], v[190:193], v[210:213], v[98:101]
	v_mfma_f32_16x16x32_bf16 v[90:93], v[182:185], v[218:221], v[90:93]
	v_mfma_f32_16x16x32_bf16 v[82:85], v[190:193], v[218:221], v[82:85]
	v_mfma_f32_16x16x32_bf16 v[74:77], v[182:185], v[226:229], v[74:77]
	v_mfma_f32_16x16x32_bf16 v[66:69], v[190:193], v[226:229], v[66:69]
	s_setprio 0
	s_barrier
	s_add_i32 s65, s52, s42
	s_mov_b32 m0, s65
	ds_read_b128 v[194:197], v159 offset:16384
	ds_read_b128 v[202:205], v159 offset:17408
	ds_read_b128 v[206:209], v159 offset:18432
	ds_read_b128 v[210:213], v159 offset:19456
	ds_read_b128 v[214:217], v159 offset:20480
	ds_read_b128 v[218:221], v159 offset:21504
	ds_read_b128 v[222:225], v159 offset:22528
	ds_read_b128 v[226:229], v159 offset:23552
	global_load_lds_dwordx4 v134, s[26:27]
	s_add_i32 m0, s65, 0x2000
	s_add_u32 s66, s26, 0x80000
	s_addc_u32 s67, s27, 0
	s_add_i32 s65, s53, s42
	global_load_lds_dwordx4 v130, s[26:27]
	s_mov_b32 m0, s65
	s_nop 0
	global_load_lds_dwordx4 v134, s[66:67]
	s_add_i32 m0, s65, 0x2000
	s_nop 0
	global_load_lds_dwordx4 v130, s[66:67]
	s_waitcnt vmcnt(6)
	s_waitcnt lgkmcnt(0)
	s_barrier
	s_setprio 1
	s_waitcnt lgkmcnt(0)
	v_mfma_f32_16x16x32_bf16 v[62:65], v[162:165], v[194:197], v[62:65]
	v_mfma_f32_16x16x32_bf16 v[54:57], v[170:173], v[194:197], v[54:57]
	v_mfma_f32_16x16x32_bf16 v[46:49], v[162:165], v[206:209], v[46:49]
	v_mfma_f32_16x16x32_bf16 v[38:41], v[170:173], v[206:209], v[38:41]
	v_mfma_f32_16x16x32_bf16 v[30:33], v[162:165], v[214:217], v[30:33]
	v_mfma_f32_16x16x32_bf16 v[22:25], v[170:173], v[214:217], v[22:25]
	v_mfma_f32_16x16x32_bf16 v[14:17], v[162:165], v[222:225], v[14:17]
	v_mfma_f32_16x16x32_bf16 v[6:9], v[170:173], v[222:225], v[6:9]
	v_mfma_f32_16x16x32_bf16 v[62:65], v[166:169], v[202:205], v[62:65]
	v_mfma_f32_16x16x32_bf16 v[54:57], v[174:177], v[202:205], v[54:57]
	v_mfma_f32_16x16x32_bf16 v[46:49], v[166:169], v[210:213], v[46:49]
	v_mfma_f32_16x16x32_bf16 v[38:41], v[174:177], v[210:213], v[38:41]
	v_mfma_f32_16x16x32_bf16 v[30:33], v[166:169], v[218:221], v[30:33]
	v_mfma_f32_16x16x32_bf16 v[22:25], v[174:177], v[218:221], v[22:25]
	v_mfma_f32_16x16x32_bf16 v[14:17], v[166:169], v[226:229], v[14:17]
	v_mfma_f32_16x16x32_bf16 v[6:9], v[174:177], v[226:229], v[6:9]
	s_setprio 0
	s_setprio 1
	v_mfma_f32_16x16x32_bf16 v[58:61], v[178:181], v[194:197], v[58:61]
	v_mfma_f32_16x16x32_bf16 v[50:53], v[186:189], v[194:197], v[50:53]
	v_mfma_f32_16x16x32_bf16 v[42:45], v[178:181], v[206:209], v[42:45]
	v_mfma_f32_16x16x32_bf16 v[34:37], v[186:189], v[206:209], v[34:37]
	v_mfma_f32_16x16x32_bf16 v[26:29], v[178:181], v[214:217], v[26:29]
	v_mfma_f32_16x16x32_bf16 v[18:21], v[186:189], v[214:217], v[18:21]
	v_mfma_f32_16x16x32_bf16 v[10:13], v[178:181], v[222:225], v[10:13]
	v_mfma_f32_16x16x32_bf16 v[2:5], v[186:189], v[222:225], v[2:5]
	v_mfma_f32_16x16x32_bf16 v[58:61], v[182:185], v[202:205], v[58:61]
	v_mfma_f32_16x16x32_bf16 v[50:53], v[190:193], v[202:205], v[50:53]
	v_mfma_f32_16x16x32_bf16 v[42:45], v[182:185], v[210:213], v[42:45]
	v_mfma_f32_16x16x32_bf16 v[34:37], v[190:193], v[210:213], v[34:37]
	v_mfma_f32_16x16x32_bf16 v[26:29], v[182:185], v[218:221], v[26:29]
	v_mfma_f32_16x16x32_bf16 v[18:21], v[190:193], v[218:221], v[18:21]
	v_mfma_f32_16x16x32_bf16 v[10:13], v[182:185], v[226:229], v[10:13]
	v_mfma_f32_16x16x32_bf16 v[2:5], v[190:193], v[226:229], v[2:5]
	s_setprio 0
	s_barrier
; #define PG8_STAGE(bufoff, gbase, voff) do { _Pragma("unroll") for (int _i = 0; _i < 2; ++_i) \
;         __builtin_amdgcn_global_load_lds((const unsigned*)((const char*)(gbase) + (voff)[_i]), (PG8_LAS unsigned*)(lds + (bufoff) + ldsw + _i * 8192), 16, 0, 0); } while (0)
; #define PG8_LDA(dst, b, h) do { _Pragma("unroll") for (int m = 0; m < 4; ++m) _Pragma("unroll") for (int k = 0; k < 2; ++k) dst[m][k] = *(const PG8_LAS bf16x8*)(lds + PG8_SA(b, h) + aoff + m * 2048 + k * 1024); } while (0)
; #define PG8_LDB(dst, b, h) do { _Pragma("unroll") for (int n = 0; n < 2; ++n) _Pragma("unroll") for (int k = 0; k < 2; ++k) dst[n][k] = *(const PG8_LAS bf16x8*)(lds + PG8_SB(b, h) + boff + n * 2048 + k * 1024); } while (0)
; #define PG8_MMA(ai, bj, At, Bt) do { __builtin_amdgcn_s_setprio(1); _Pragma("unroll") for (int m = 0; m < 4; ++m) _Pragma("unroll") for (int n = 0; n < 2; ++n) _Pragma("unroll") for (int k = 0; k < 2; ++k) \
;         acc[ai][bj][m][n] = __builtin_amdgcn_mfma_f32_16x16x32_bf16(Bt[n][k], At[m][k], acc[ai][bj][m][n], 0, 0, 0); __builtin_amdgcn_s_setprio(0); } while (0)
; #define PG8_WAIT_V(n) asm volatile("s_waitcnt vmcnt(" #n ")" ::: "memory")
; #define PG8_WAIT_L(n) asm volatile("s_waitcnt lgkmcnt(" #n ")" ::: "memory")
; #define PG8_BAR __builtin_amdgcn_s_barrier()
; #define PG8_SCHED __builtin_amdgcn_sched_barrier(0)
; template <class Epi, class Sched, bool ALIGN_EPI = false, bool SP2 = false>
; __device__ __forceinline__ void gemm_phase(PG8_LAS unsigned char* lds, const Gemm g, const Sched& S, const Epi& E) {
;     ...
;             PG8_LDB(B0, 1, 0); PG8_LDB(B1, 1, 1); PG8_SCHED; PG8_LDA(At, 1, 0); PG8_STAGE(PG8_SA(0, 1), a2 + hstep, voffA);
;             PG8_WAIT_V(8); PG8_WAIT_L(0); PG8_BAR; PG8_MMA(0, 0, At, B0); PG8_MMA(0, 1, At, B1); PG8_BAR; PG8_SCHED;
;             PG8_LDA(At, 1, 1); PG8_STAGE(PG8_SB(1, 0), b3, voffB); PG8_STAGE(PG8_SB(1, 1), b3 + hstep, voffB); PG8_STAGE(PG8_SA(1, 0), a3, voffA);
;             PG8_WAIT_V(8); PG8_WAIT_L(0); PG8_BAR; PG8_MMA(1, 0, At, B0); PG8_MMA(1, 1, At, B1); PG8_BAR; PG8_SCHED;
	s_add_i32 s65, 0, 0x18000
	s_add_i32 s66, 0, 0x1c000
	ds_read_b128 v[162:165], v238 offset:32768
	ds_read_b128 v[166:169], v238 offset:33792
	ds_read_b128 v[170:173], v238 offset:34816
	ds_read_b128 v[174:177], v238 offset:35840
	ds_read_b128 v[178:181], v238 offset:49152
	ds_read_b128 v[182:185], v238 offset:50176
	ds_read_b128 v[186:189], v238 offset:51200
	ds_read_b128 v[190:193], v238 offset:52224
	s_mov_b32 m0, s23
	s_nop 0
	global_load_lds_dwordx4 v136, s[36:37]
	s_mov_b32 m0, s45
	s_nop 0
	global_load_lds_dwordx4 v132, s[36:37]
	s_add_u32 s36, s36, 0x80000
	s_addc_u32 s37, s37, 0
	s_mov_b32 m0, s46
	ds_read_b128 v[194:197], v159 offset:32768
	ds_read_b128 v[202:205], v159 offset:33792
	ds_read_b128 v[206:209], v159 offset:34816
	ds_read_b128 v[210:213], v159 offset:35840
	ds_read_b128 v[214:217], v159 offset:36864
	ds_read_b128 v[218:221], v159 offset:37888
	ds_read_b128 v[222:225], v159 offset:38912
	ds_read_b128 v[226:229], v159 offset:39936
	global_load_lds_dwordx4 v136, s[36:37]
	s_mov_b32 m0, s47
	s_nop 0
	global_load_lds_dwordx4 v132, s[36:37]
	s_waitcnt vmcnt(8)
	s_waitcnt lgkmcnt(0)
	s_barrier
	s_setprio 1
	s_waitcnt lgkmcnt(0)
	v_mfma_f32_16x16x32_bf16 v[126:129], v[162:165], v[194:197], v[126:129]
	v_mfma_f32_16x16x32_bf16 v[118:121], v[170:173], v[194:197], v[118:121]
	v_mfma_f32_16x16x32_bf16 v[110:113], v[162:165], v[206:209], v[110:113]
	v_mfma_f32_16x16x32_bf16 v[102:105], v[170:173], v[206:209], v[102:105]
	v_mfma_f32_16x16x32_bf16 v[94:97], v[162:165], v[214:217], v[94:97]
	v_mfma_f32_16x16x32_bf16 v[86:89], v[170:173], v[214:217], v[86:89]
	v_mfma_f32_16x16x32_bf16 v[78:81], v[162:165], v[222:225], v[78:81]
	v_mfma_f32_16x16x32_bf16 v[70:73], v[170:173], v[222:225], v[70:73]
	v_mfma_f32_16x16x32_bf16 v[126:129], v[166:169], v[202:205], v[126:129]
	v_mfma_f32_16x16x32_bf16 v[118:121], v[174:177], v[202:205], v[118:121]
	v_mfma_f32_16x16x32_bf16 v[110:113], v[166:169], v[210:213], v[110:113]
	v_mfma_f32_16x16x32_bf16 v[102:105], v[174:177], v[210:213], v[102:105]
	v_mfma_f32_16x16x32_bf16 v[94:97], v[166:169], v[218:221], v[94:97]
	v_mfma_f32_16x16x32_bf16 v[86:89], v[174:177], v[218:221], v[86:89]
	v_mfma_f32_16x16x32_bf16 v[78:81], v[166:169], v[226:229], v[78:81]
	v_mfma_f32_16x16x32_bf16 v[70:73], v[174:177], v[226:229], v[70:73]
	s_setprio 0
	s_setprio 1
	v_mfma_f32_16x16x32_bf16 v[122:125], v[178:181], v[194:197], v[122:125]
	v_mfma_f32_16x16x32_bf16 v[114:117], v[186:189], v[194:197], v[114:117]
	v_mfma_f32_16x16x32_bf16 v[106:109], v[178:181], v[206:209], v[106:109]
	v_mfma_f32_16x16x32_bf16 v[98:101], v[186:189], v[206:209], v[98:101]
	v_mfma_f32_16x16x32_bf16 v[90:93], v[178:181], v[214:217], v[90:93]
	v_mfma_f32_16x16x32_bf16 v[82:85], v[186:189], v[214:217], v[82:85]
	v_mfma_f32_16x16x32_bf16 v[74:77], v[178:181], v[222:225], v[74:77]
	v_mfma_f32_16x16x32_bf16 v[66:69], v[186:189], v[222:225], v[66:69]
	v_mfma_f32_16x16x32_bf16 v[122:125], v[182:185], v[202:205], v[122:125]
	v_mfma_f32_16x16x32_bf16 v[114:117], v[190:193], v[202:205], v[114:117]
	v_mfma_f32_16x16x32_bf16 v[106:109], v[182:185], v[210:213], v[106:109]
	v_mfma_f32_16x16x32_bf16 v[98:101], v[190:193], v[210:213], v[98:101]
	v_mfma_f32_16x16x32_bf16 v[90:93], v[182:185], v[218:221], v[90:93]
	v_mfma_f32_16x16x32_bf16 v[82:85], v[190:193], v[218:221], v[82:85]
	v_mfma_f32_16x16x32_bf16 v[74:77], v[182:185], v[226:229], v[74:77]
	v_mfma_f32_16x16x32_bf16 v[66:69], v[190:193], v[226:229], v[66:69]
	s_setprio 0
	s_barrier
	s_add_i32 s36, s65, s42
	s_add_u32 s26, s26, 0x80
	s_addc_u32 s27, s27, 0
	s_mov_b32 m0, s36
	ds_read_b128 v[194:197], v159 offset:49152
	ds_read_b128 v[202:205], v159 offset:50176
	ds_read_b128 v[206:209], v159 offset:51200
	ds_read_b128 v[210:213], v159 offset:52224
	ds_read_b128 v[214:217], v159 offset:53248
	ds_read_b128 v[218:221], v159 offset:54272
	ds_read_b128 v[222:225], v159 offset:55296
	ds_read_b128 v[226:229], v159 offset:56320
	global_load_lds_dwordx4 v134, s[26:27]
	s_add_i32 m0, s36, 0x2000
	s_add_i32 s36, s66, s42
	global_load_lds_dwordx4 v130, s[26:27]
	s_add_u32 s26, s26, 0x80000
	s_addc_u32 s27, s27, 0
	s_mov_b32 m0, s36
	s_nop 0
	global_load_lds_dwordx4 v134, s[26:27]
	s_add_i32 m0, s36, 0x2000
	s_nop 0
	global_load_lds_dwordx4 v130, s[26:27]
	s_waitcnt vmcnt(6)
	s_waitcnt lgkmcnt(0)
	s_barrier
	s_setprio 1
	s_waitcnt lgkmcnt(0)
	v_mfma_f32_16x16x32_bf16 v[62:65], v[162:165], v[194:197], v[62:65]
	v_mfma_f32_16x16x32_bf16 v[54:57], v[170:173], v[194:197], v[54:57]
	v_mfma_f32_16x16x32_bf16 v[46:49], v[162:165], v[206:209], v[46:49]
	v_mfma_f32_16x16x32_bf16 v[38:41], v[170:173], v[206:209], v[38:41]
	v_mfma_f32_16x16x32_bf16 v[30:33], v[162:165], v[214:217], v[30:33]
	v_mfma_f32_16x16x32_bf16 v[22:25], v[170:173], v[214:217], v[22:25]
	v_mfma_f32_16x16x32_bf16 v[14:17], v[162:165], v[222:225], v[14:17]
	v_mfma_f32_16x16x32_bf16 v[6:9], v[170:173], v[222:225], v[6:9]
	v_mfma_f32_16x16x32_bf16 v[62:65], v[166:169], v[202:205], v[62:65]
	v_mfma_f32_16x16x32_bf16 v[54:57], v[174:177], v[202:205], v[54:57]
	v_mfma_f32_16x16x32_bf16 v[46:49], v[166:169], v[210:213], v[46:49]
	v_mfma_f32_16x16x32_bf16 v[38:41], v[174:177], v[210:213], v[38:41]
	v_mfma_f32_16x16x32_bf16 v[30:33], v[166:169], v[218:221], v[30:33]
	v_mfma_f32_16x16x32_bf16 v[22:25], v[174:177], v[218:221], v[22:25]
	v_mfma_f32_16x16x32_bf16 v[14:17], v[166:169], v[226:229], v[14:17]
	v_mfma_f32_16x16x32_bf16 v[6:9], v[174:177], v[226:229], v[6:9]
	s_setprio 0
	s_setprio 1
	v_mfma_f32_16x16x32_bf16 v[58:61], v[178:181], v[194:197], v[58:61]
	v_mfma_f32_16x16x32_bf16 v[50:53], v[186:189], v[194:197], v[50:53]
	v_mfma_f32_16x16x32_bf16 v[42:45], v[178:181], v[206:209], v[42:45]
	v_mfma_f32_16x16x32_bf16 v[34:37], v[186:189], v[206:209], v[34:37]
	v_mfma_f32_16x16x32_bf16 v[26:29], v[178:181], v[214:217], v[26:29]
	v_mfma_f32_16x16x32_bf16 v[18:21], v[186:189], v[214:217], v[18:21]
	v_mfma_f32_16x16x32_bf16 v[10:13], v[178:181], v[222:225], v[10:13]
	v_mfma_f32_16x16x32_bf16 v[2:5], v[186:189], v[222:225], v[2:5]
	v_mfma_f32_16x16x32_bf16 v[58:61], v[182:185], v[202:205], v[58:61]
	v_mfma_f32_16x16x32_bf16 v[50:53], v[190:193], v[202:205], v[50:53]
	v_mfma_f32_16x16x32_bf16 v[42:45], v[182:185], v[210:213], v[42:45]
	v_mfma_f32_16x16x32_bf16 v[34:37], v[190:193], v[210:213], v[34:37]
	v_mfma_f32_16x16x32_bf16 v[26:29], v[182:185], v[218:221], v[26:29]
	v_mfma_f32_16x16x32_bf16 v[18:21], v[190:193], v[218:221], v[18:21]
	v_mfma_f32_16x16x32_bf16 v[10:13], v[182:185], v[226:229], v[10:13]
	v_mfma_f32_16x16x32_bf16 v[2:5], v[190:193], v[226:229], v[2:5]
	s_setprio 0
	s_barrier
	s_add_i32 s64, s64, 2
	s_add_u32 s62, s62, 0x100
	s_addc_u32 s63, s63, 0
	s_add_u32 s24, s24, 0x100
	s_addc_u32 s25, s25, 0
	s_cmp_gt_u32 s64, 29
	s_cbranch_scc1 .LBB0_695
